# NSA sliding-window loop software-pipelined (softmax vs PV+QK segments alternate between wave halves, triple-buffered tiles, two-sided edge masks)
# speedup vs baseline: 1.0477x; 1.0061x over previous
;     ...
;     if (probe != 1) { kv_gload<DV, HAS_V>(st, Kb, VTb, ldv, jn * 64); kv_sstore<DV, HAS_V>(st, lds); }
;     __syncthreads();
;     ...
;     {
;         const bf16_t* Kw = (const bf16_t*)(p.ws + OFF_KW) + (size_t)bg * 4096 * 64;
;         const bf16_t* VwT = (const bf16_t*)(p.ws + OFF_VWT) + (size_t)bg * 64 * 4096;
;         const int tlo = (q0 > 511 ? q0 - 511 : 0) >> 6, thi = (q0 + 63) >> 6;
;         f32x16 o[2];
; #pragma unroll
;         for (int dt = 0; dt < 2; ++dt)
; #pragma unroll
;             for (int i = 0; i < 16; ++i) o[dt][i] = 0.f;
;         float m = -1e30f; f32x16 lv;
; #pragma unroll
;         for (int i = 0; i < 16; ++i) lv[i] = 0.f;
;         kv_loop<64, true>(lds, Kw, VwT, 4096, thi - tlo + 1, tlo, inc, [&](int j, const unsigned char* sb) {
.LBB0_559:
	s_or_b64 exec, exec, s[4:5]
	v_sub_u32_e32 v66, 0xdc0, v130
	s_movk_i32 s2, 0x1ff
	v_ashrrev_i32_e32 v66, 6, v66
	v_cmp_lt_i32_e32 vcc, s2, v123
	v_mov_b32_e32 v67, v173
	v_mov_b32_e32 v175, v173
	s_waitcnt vmcnt(1)
	v_cndmask_b32_e32 v114, 0, v66, vcc
	v_lshlrev_b32_e32 v66, 1, v82
	v_lshl_add_u64 v[116:117], s[96:97], 0, v[66:67]
	s_waitcnt vmcnt(0)
	v_lshl_add_u64 v[118:119], s[82:83], 0, v[66:67]
	v_lshl_add_u32 v66, v114, 6, v187
	v_ashrrev_i32_e32 v67, 31, v66
	v_lshlrev_b64 v[66:67], 7, v[66:67]
	v_ashrrev_i32_e32 v115, 31, v114
	v_lshl_add_u64 v[66:67], v[118:119], 0, v[66:67]
	v_lshlrev_b64 v[68:69], 13, v[114:115]
	v_lshl_add_u64 v[66:67], v[66:67], 0, v[172:173]
	v_lshl_add_u64 v[68:69], v[116:117], 0, v[68:69]
	v_lshl_add_u64 v[68:69], v[68:69], 0, v[174:175]
	global_load_dwordx4 v[162:165], v[66:67], off
	global_load_dwordx4 v[166:169], v[68:69], off
	v_lshrrev_b32_e32 v66, 6, v123
	v_mov_b32_e32 v98, v173
	v_mov_b32_e32 v99, v173
	v_mov_b32_e32 v100, v173
	v_mov_b32_e32 v101, v173
	v_mov_b32_e32 v102, v173
	v_mov_b32_e32 v103, v173
	v_mov_b32_e32 v104, v173
	v_mov_b32_e32 v105, v173
	v_mov_b32_e32 v106, v173
	v_mov_b32_e32 v107, v173
	v_mov_b32_e32 v108, v173
	v_mov_b32_e32 v109, v173
	v_mov_b32_e32 v110, v173
	v_mov_b32_e32 v111, v173
	v_mov_b32_e32 v112, v173
	v_mov_b32_e32 v113, v173
	v_mov_b64_e32 v[82:83], v[98:99]
	v_sub_u32_e32 v206, v66, v114
	v_mov_b64_e32 v[66:67], v[98:99]
	v_mov_b64_e32 v[84:85], v[100:101]
	v_mov_b64_e32 v[86:87], v[102:103]
	v_mov_b64_e32 v[88:89], v[104:105]
	v_mov_b64_e32 v[90:91], v[106:107]
	v_mov_b64_e32 v[92:93], v[108:109]
	v_mov_b64_e32 v[94:95], v[110:111]
	v_mov_b64_e32 v[96:97], v[112:113]
	v_cmp_lt_i32_e32 vcc, -1, v206
	v_mov_b64_e32 v[68:69], v[100:101]
	v_mov_b64_e32 v[70:71], v[102:103]
	v_mov_b64_e32 v[72:73], v[104:105]
	v_mov_b64_e32 v[74:75], v[106:107]
	v_mov_b64_e32 v[76:77], v[108:109]
	v_mov_b64_e32 v[78:79], v[110:111]
	v_mov_b64_e32 v[80:81], v[112:113]
	s_waitcnt vmcnt(1)
	ds_write_b128 v198, v[162:165]
	s_waitcnt vmcnt(0)
	ds_write2_b64 v199, v[166:167], v[168:169] offset0:128 offset1:130
	s_waitcnt lgkmcnt(0)
	s_barrier
	s_and_saveexec_b64 s[8:9], vcc
	s_cbranch_execz .LBB0_575
	v_mov_b32_e32 v80, v173
	v_mov_b32_e32 v81, v173
	v_mov_b32_e32 v66, v173
	v_mov_b32_e32 v67, v173
	v_mov_b32_e32 v68, v173
	v_mov_b32_e32 v69, v173
	v_mov_b32_e32 v70, v173
	v_mov_b32_e32 v71, v173
	v_mov_b32_e32 v72, v173
	v_mov_b32_e32 v73, v173
	v_mov_b32_e32 v74, v173
	v_mov_b32_e32 v75, v173
	v_mov_b32_e32 v76, v173
	v_mov_b32_e32 v77, v173
	v_mov_b32_e32 v78, v173
	v_mov_b32_e32 v79, v173
	v_mov_b64_e32 v[96:97], v[80:81]
	v_mov_b64_e32 v[112:113], v[80:81]
	v_lshl_add_u64 v[188:189], v[118:119], 0, v[172:173]
	v_lshl_add_u64 v[190:191], v[116:117], 0, v[174:175]
	v_or_b32_e32 v175, 31, v203
	v_add_u32_e32 v207, 0xfffffe00, v203
	v_add_u32_e32 v208, 0xfffffe1f, v203
	v_add_u32_e32 v209, 0xfffffe00, v178
	v_add_u32_e32 v210, 1, v206
	s_mov_b32 s2, 0
	v_mov_b32_e32 v211, 0xf149f2ca
	s_mov_b64 s[10:11], 0
	v_mov_b64_e32 v[94:95], v[78:79]
	v_mov_b64_e32 v[92:93], v[76:77]
	v_mov_b64_e32 v[90:91], v[74:75]
	v_mov_b64_e32 v[88:89], v[72:73]
	v_mov_b64_e32 v[86:87], v[70:71]
	v_mov_b64_e32 v[84:85], v[68:69]
	v_mov_b64_e32 v[82:83], v[66:67]
	v_mov_b64_e32 v[110:111], v[78:79]
	v_mov_b64_e32 v[108:109], v[76:77]
	v_mov_b64_e32 v[106:107], v[74:75]
	v_mov_b64_e32 v[104:105], v[72:73]
	v_mov_b64_e32 v[102:103], v[70:71]
	v_mov_b64_e32 v[100:101], v[68:69]
	v_mov_b64_e32 v[98:99], v[66:67]
	v_readfirstlane_b32 s28, v0
	v_readfirstlane_b32 s14, v114
	v_readfirstlane_b32 s12, v206
	v_readfirstlane_b32 s21, v203
	s_bfe_u32 s28, s28, 0x10008
	s_add_i32 s12, s12, 1
	s_mov_b32 s13, 0
	s_mov_b32 s18, 0
	s_movk_i32 s19, 0x4800
	s_mov_b32 s20, 0x9000
	s_cmp_lt_u32 s12, 2
	s_cbranch_scc1 .Lnw_p1
	s_add_i32 s15, s14, 1

; template <int DV, bool HAS_V>
; DI void kv_gload(KVStage<DV>& st, const bf16_t* __restrict__ Kb, const bf16_t* __restrict__ VTb, int ldv, int key0) {
;     const int tid = threadIdx.x;
;     st.k[0] = *(const u32x4*)(Kb + (size_t)(key0 + (tid >> 3)) * 64 + (tid & 7) * 8);
;     if (HAS_V) {
; #pragma unroll
;         for (int i = 0; i < DV / 64; ++i) { const int c = tid + 512 * i; st.v[i] = *(const u32x4*)(VTb + (size_t)(key0 >> 6) * (DV * 64) + c * 8); }
;     }
; }
	s_lshl_b32 s4, s15, 6
	v_add_u32_e32 v228, s4, v187
	v_mov_b32_e32 v229, v173
	v_lshlrev_b64 v[228:229], 7, v[228:229]
	v_lshl_add_u64 v[228:229], v[188:189], 0, v[228:229]
	global_load_dwordx4 v[162:165], v[228:229], off
	s_lshl_b32 s4, s15, 13
	s_mov_b32 s5, 0
	v_lshl_add_u64 v[230:231], v[190:191], 0, s[4:5]
	global_load_dwordx4 v[166:169], v[230:231], off

;     ...
;             const int k0 = j * 64;
;             if (k0 > qb + 31 || k0 + 63 <= qb - 512) return;
.Lnw_p1:
	s_lshl_b32 s6, s14, 6
	s_add_i32 s7, s21, 31
	s_cmp_le_i32 s6, s7
	s_cselect_b32 s16, 1, 0
	s_add_i32 s6, s6, 63
	s_add_i32 s7, s21, 0xfffffe00
	s_cmp_gt_i32 s6, s7
	s_cselect_b32 s7, 1, 0
	s_and_b32 s16, s16, s7

;     ...
;             if (k0 > qb + 31 || k0 + 63 <= qb - 512) return;
;             f32x16 s0, s1; attn_scores(sb, qf, r, h, s0, s1);
	s_cmp_eq_u32 s16, 0
	s_cbranch_scc1 .Lnw_p2
	v_add3_u32 v236, s18, v204, v180

; #define MFMA(a, b, c) __builtin_amdgcn_mfma_f32_32x32x16_bf16((a), (b), (c), 0, 0, 0)
; DI void attn_scores(const unsigned char* kb, const bf16x8 (&qf)[4], int r, int h, f32x16& s0, f32x16& s1) {
; #pragma unroll
;     for (int i = 0; i < 16; ++i) { s0[i] = 0.f; s1[i] = 0.f; }
; #pragma unroll
;     for (int s = 0; s < 4; ++s) {
;         const bf16x8 k0 = *(const bf16x8*)(kb + r * KP + s * 32 + h * 16);
;         const bf16x8 k1 = *(const bf16x8*)(kb + (32 + r) * KP + s * 32 + h * 16);
;         s0 = MFMA(k0, qf[s], s0); s1 = MFMA(k1, qf[s], s1);
;     }
; }
	ds_read_b128 v[228:231], v236 offset:0
	ds_read_b128 v[232:235], v236 offset:4608
	ds_read_b128 v[206:209], v236 offset:32
	s_waitcnt lgkmcnt(2)
	v_mfma_f32_32x32x16_bf16 v[130:145], v[228:231], v[146:149], 0
	ds_read_b128 v[228:231], v236 offset:4640
	s_waitcnt lgkmcnt(2)
	v_mfma_f32_32x32x16_bf16 v[114:129], v[232:235], v[146:149], 0
	ds_read_b128 v[232:235], v236 offset:64
	s_waitcnt lgkmcnt(2)
	v_mfma_f32_32x32x16_bf16 v[130:145], v[206:209], v[150:153], v[130:145]
	ds_read_b128 v[206:209], v236 offset:4672
	s_waitcnt lgkmcnt(2)
	v_mfma_f32_32x32x16_bf16 v[114:129], v[228:231], v[150:153], v[114:129]
	ds_read_b128 v[228:231], v236 offset:96
	s_waitcnt lgkmcnt(2)
	v_mfma_f32_32x32x16_bf16 v[130:145], v[232:235], v[154:157], v[130:145]
	ds_read_b128 v[232:235], v236 offset:4704
	s_waitcnt lgkmcnt(2)
	v_mfma_f32_32x32x16_bf16 v[114:129], v[206:209], v[154:157], v[114:129]
	s_waitcnt lgkmcnt(1)
	v_mfma_f32_32x32x16_bf16 v[130:145], v[228:231], v[158:161], v[130:145]
	s_waitcnt lgkmcnt(0)
	v_mfma_f32_32x32x16_bf16 v[114:129], v[232:235], v[158:161], v[114:129]
.Lnw_p2:
	s_cmp_lt_u32 s12, 2
	s_cbranch_scc1 .Lnw_p3
	s_waitcnt vmcnt(0)

; template <int DV, bool HAS_V>
; DI void kv_sstore(const KVStage<DV>& st, unsigned char* buf) {
;     const int tid = threadIdx.x;
;     *(u32x4*)(buf + (tid >> 3) * KP + (tid & 7) * 16) = st.k[0];
;     if (HAS_V) {
; #pragma unroll
;         for (int i = 0; i < DV / 64; ++i) {
;             const int c = tid + 512 * i, kc = c & 7; unsigned char* q = buf + KT_BYTES + (c >> 3) * VP + (kc >> 1) * 32 + (kc & 1) * 8;
;             u32x2 lo, hi; lo.x = st.v[i].x; lo.y = st.v[i].y; hi.x = st.v[i].z; hi.y = st.v[i].w;
;             *(u32x2*)q = lo; *(u32x2*)(q + 16) = hi;
;         }
;     }
; }
	v_add_u32_e32 v192, s19, v194
	v_add_u32_e32 v193, v192, v195
	v_add3_u32 v192, v192, v196, v197
	v_add_u32_e32 v192, 0x2000, v192
	ds_write_b128 v193, v[162:165]
	ds_write2_b64 v192, v[166:167], v[168:169] offset0:128 offset1:130

;     ...
;     for (int i = 0; i < nt; ++i) {
;         const int j = jn;
;         const bool more = (i + 1 < nt);
;         if (more) { jn = next(j); if (probe != 1) kv_gload<DV, HAS_V>(st, Kb, VTb, ldv, jn * 64); }
	s_cmp_lt_u32 s12, 3
	s_cbranch_scc1 .Lnw_p3
	s_add_i32 s15, s14, 2

; template <int DV, bool HAS_V>
; DI void kv_gload(KVStage<DV>& st, const bf16_t* __restrict__ Kb, const bf16_t* __restrict__ VTb, int ldv, int key0) {
;     const int tid = threadIdx.x;
;     st.k[0] = *(const u32x4*)(Kb + (size_t)(key0 + (tid >> 3)) * 64 + (tid & 7) * 8);
;     if (HAS_V) {
; #pragma unroll
;         for (int i = 0; i < DV / 64; ++i) { const int c = tid + 512 * i; st.v[i] = *(const u32x4*)(VTb + (size_t)(key0 >> 6) * (DV * 64) + c * 8); }
;     }
; }
	s_lshl_b32 s4, s15, 6
	v_add_u32_e32 v228, s4, v187
	v_mov_b32_e32 v229, v173
	v_lshlrev_b64 v[228:229], 7, v[228:229]
	v_lshl_add_u64 v[228:229], v[188:189], 0, v[228:229]
	global_load_dwordx4 v[162:165], v[228:229], off
	s_lshl_b32 s4, s15, 13
	s_mov_b32 s5, 0
	v_lshl_add_u64 v[230:231], v[190:191], 0, s[4:5]
	global_load_dwordx4 v[166:169], v[230:231], off


; DI int crow(int i, int h) { return (i & 3) + 8 * (i >> 2) + 4 * h; }
; #define NEG_INF (-__builtin_inff())
;     ...
;         kv_loop<64, true>(lds, Kw, VwT, 4096, thi - tlo + 1, tlo, inc, [&](int j, const unsigned char* sb) {
;             const int k0 = j * 64;
;             if (k0 > qb + 31 || k0 + 63 <= qb - 512) return;
;             f32x16 s0, s1; attn_scores(sb, qf, r, h, s0, s1);
;             if (!(k0 + 63 <= qb && k0 > qb + 31 - 512)) {
; #pragma unroll
;                 for (int i = 0; i < 16; ++i) {
;                     const int ka = k0 + crow(i, h), kb2 = ka + 32;
;                     if (!(ka <= qpos && ka > qpos - 512)) s0[i] = NEG_INF;
;                     if (!(kb2 <= qpos && kb2 > qpos - 512)) s1[i] = NEG_INF;
;                 }
;             }
.Lnw_loop:
	s_cmp_eq_u32 s16, 0
	s_cbranch_scc1 .Lnw_xdone
	s_nop 3
	s_lshl_b32 s6, s14, 6
	s_add_i32 s7, s6, 63
	s_cmp_gt_i32 s7, s21
	s_cbranch_scc1 .Lnw_mask
	s_add_i32 s7, s21, 0xfffffe1f
	s_cmp_le_i32 s6, s7
	s_cbranch_scc0 .Lnw_nomask
.Lnw_mask:
	v_subrev_u32_e32 v192, s6, v178
	v_sub_u32_e32 v192, v192, v181
	v_mov_b32_e32 v210, 0x200

; DI int crow(int i, int h) { return (i & 3) + 8 * (i >> 2) + 4 * h; }
; #define NEG_INF (-__builtin_inff())
;     ...
;             if (!(k0 + 63 <= qb && k0 > qb + 31 - 512)) {
; #pragma unroll
;                 for (int i = 0; i < 16; ++i) {
;                     const int ka = k0 + crow(i, h), kb2 = ka + 32;
;                     if (!(ka <= qpos && ka > qpos - 512)) s0[i] = NEG_INF;
;                     if (!(kb2 <= qpos && kb2 > qpos - 512)) s1[i] = NEG_INF;
;                 }
;             }
	v_subrev_u32_e32 v193, 0, v192
	v_cmp_gt_u32_e32 vcc, v210, v193
	s_nop 1
	v_cndmask_b32_e32 v130, v200, v130, vcc
	v_subrev_u32_e32 v193, 32, v192
	v_cmp_gt_u32_e32 vcc, v210, v193
	s_nop 1
	v_cndmask_b32_e32 v114, v200, v114, vcc
	v_subrev_u32_e32 v193, 1, v192
	v_cmp_gt_u32_e32 vcc, v210, v193
	s_nop 1
	v_cndmask_b32_e32 v131, v200, v131, vcc
	v_subrev_u32_e32 v193, 33, v192
	v_cmp_gt_u32_e32 vcc, v210, v193
	s_nop 1
	v_cndmask_b32_e32 v115, v200, v115, vcc
	v_subrev_u32_e32 v193, 2, v192
	v_cmp_gt_u32_e32 vcc, v210, v193
	s_nop 1
	v_cndmask_b32_e32 v132, v200, v132, vcc
	v_subrev_u32_e32 v193, 34, v192
	v_cmp_gt_u32_e32 vcc, v210, v193
	s_nop 1
	v_cndmask_b32_e32 v116, v200, v116, vcc
	v_subrev_u32_e32 v193, 3, v192
	v_cmp_gt_u32_e32 vcc, v210, v193
	s_nop 1
	v_cndmask_b32_e32 v133, v200, v133, vcc
	v_subrev_u32_e32 v193, 35, v192
	v_cmp_gt_u32_e32 vcc, v210, v193
	s_nop 1
	v_cndmask_b32_e32 v117, v200, v117, vcc
	v_subrev_u32_e32 v193, 8, v192
	v_cmp_gt_u32_e32 vcc, v210, v193
	s_nop 1
	v_cndmask_b32_e32 v134, v200, v134, vcc
	v_subrev_u32_e32 v193, 40, v192
	v_cmp_gt_u32_e32 vcc, v210, v193
	s_nop 1
	v_cndmask_b32_e32 v118, v200, v118, vcc
	v_subrev_u32_e32 v193, 9, v192
	v_cmp_gt_u32_e32 vcc, v210, v193
	s_nop 1
	v_cndmask_b32_e32 v135, v200, v135, vcc
	v_subrev_u32_e32 v193, 41, v192
	v_cmp_gt_u32_e32 vcc, v210, v193
	s_nop 1
	v_cndmask_b32_e32 v119, v200, v119, vcc
	v_subrev_u32_e32 v193, 10, v192
	v_cmp_gt_u32_e32 vcc, v210, v193
	s_nop 1
	v_cndmask_b32_e32 v136, v200, v136, vcc
	v_subrev_u32_e32 v193, 42, v192
	v_cmp_gt_u32_e32 vcc, v210, v193
	s_nop 1
	v_cndmask_b32_e32 v120, v200, v120, vcc
	v_subrev_u32_e32 v193, 11, v192
	v_cmp_gt_u32_e32 vcc, v210, v193
	s_nop 1
	v_cndmask_b32_e32 v137, v200, v137, vcc
	v_subrev_u32_e32 v193, 43, v192
	v_cmp_gt_u32_e32 vcc, v210, v193
	s_nop 1
	v_cndmask_b32_e32 v121, v200, v121, vcc
	v_subrev_u32_e32 v193, 16, v192
	v_cmp_gt_u32_e32 vcc, v210, v193
	s_nop 1
	v_cndmask_b32_e32 v138, v200, v138, vcc
	v_subrev_u32_e32 v193, 48, v192
	v_cmp_gt_u32_e32 vcc, v210, v193
	s_nop 1
	v_cndmask_b32_e32 v122, v200, v122, vcc
	v_subrev_u32_e32 v193, 17, v192
	v_cmp_gt_u32_e32 vcc, v210, v193
	s_nop 1
	v_cndmask_b32_e32 v139, v200, v139, vcc
	v_subrev_u32_e32 v193, 49, v192
	v_cmp_gt_u32_e32 vcc, v210, v193
	s_nop 1
	v_cndmask_b32_e32 v123, v200, v123, vcc
	v_subrev_u32_e32 v193, 18, v192
	v_cmp_gt_u32_e32 vcc, v210, v193
	s_nop 1
	v_cndmask_b32_e32 v140, v200, v140, vcc
	v_subrev_u32_e32 v193, 50, v192
	v_cmp_gt_u32_e32 vcc, v210, v193
	s_nop 1
	v_cndmask_b32_e32 v124, v200, v124, vcc
	v_subrev_u32_e32 v193, 19, v192
	v_cmp_gt_u32_e32 vcc, v210, v193
	s_nop 1
	v_cndmask_b32_e32 v141, v200, v141, vcc
	v_subrev_u32_e32 v193, 51, v192
	v_cmp_gt_u32_e32 vcc, v210, v193
	s_nop 1
	v_cndmask_b32_e32 v125, v200, v125, vcc
	v_subrev_u32_e32 v193, 24, v192
	v_cmp_gt_u32_e32 vcc, v210, v193
	s_nop 1
	v_cndmask_b32_e32 v142, v200, v142, vcc
	v_subrev_u32_e32 v193, 56, v192
	v_cmp_gt_u32_e32 vcc, v210, v193
	s_nop 1
	v_cndmask_b32_e32 v126, v200, v126, vcc
	v_subrev_u32_e32 v193, 25, v192
	v_cmp_gt_u32_e32 vcc, v210, v193
	s_nop 1
	v_cndmask_b32_e32 v143, v200, v143, vcc
	v_subrev_u32_e32 v193, 57, v192
	v_cmp_gt_u32_e32 vcc, v210, v193
	s_nop 1
	v_cndmask_b32_e32 v127, v200, v127, vcc
	v_subrev_u32_e32 v193, 26, v192
	v_cmp_gt_u32_e32 vcc, v210, v193
	s_nop 1
	v_cndmask_b32_e32 v144, v200, v144, vcc
	v_subrev_u32_e32 v193, 58, v192
	v_cmp_gt_u32_e32 vcc, v210, v193
	s_nop 1
	v_cndmask_b32_e32 v128, v200, v128, vcc
	v_subrev_u32_e32 v193, 27, v192
	v_cmp_gt_u32_e32 vcc, v210, v193
	s_nop 1
	v_cndmask_b32_e32 v145, v200, v145, vcc
	v_subrev_u32_e32 v193, 59, v192
	v_cmp_gt_u32_e32 vcc, v210, v193
	s_nop 1
	v_cndmask_b32_e32 v129, v200, v129, vcc
; DI float fast_exp2(float x) { return __builtin_amdgcn_exp2f(x); }
; DI float xhalf_max(float x) { auto rr = __builtin_amdgcn_permlane32_swap(__float_as_uint(x), __float_as_uint(x), false, false); return fmaxf(__uint_as_float(rr[0]), __uint_as_float(rr[1])); }
; #define NEG_INF (-__builtin_inff())
; template <int DV>
; DI void attn_softmax_pv(f32x16& s0, f32x16& s1, float& m, f32x16& lv, f32x16 (&o)[DV / 32], const unsigned char* vb, int r, int h, bool on = true) {
;     s0 = s0 * SM_C; s1 = s1 * SM_C;
;     const f32x16 t = __builtin_elementwise_max(s0, s1);
;     float mx = fmaxf(fmaxf(fmaxf(t[0], t[1]), fmaxf(t[2], t[3])), fmaxf(fmaxf(t[4], t[5]), fmaxf(t[6], t[7])));
;     mx = fmaxf(mx, fmaxf(fmaxf(fmaxf(t[8], t[9]), fmaxf(t[10], t[11])), fmaxf(fmaxf(t[12], t[13]), fmaxf(t[14], t[15]))));
;     mx = on ? mx : NEG_INF;
;     mx = xhalf_max(mx);
;     if (!__all(mx - m <= SM_THR)) {
;         const float mn = fmaxf(m, mx);
;         const float alpha = fast_exp2(m - mn);
;         lv = lv * alpha; m = mn;
; #pragma unroll
;         for (int dt = 0; dt < DV / 32; ++dt) o[dt] = o[dt] * alpha;
;     }
;     const float msub = on ? m : __builtin_inff();
;     s0 = s0 - msub; s1 = s1 - msub;
; #pragma unroll
;     for (int i = 0; i < 16; ++i) { s0[i] = fast_exp2(s0[i]); s1[i] = fast_exp2(s1[i]); }
;     lv = lv + (s0 + s1);
;     bf16x8 pf[2][2]; pack_p(s0, s1, pf);
;     attn_pv<DV>(vb, pf, r, h, o);
; }
;     ...
;             attn_softmax_pv<64>(s0, s1, m, lv, o, sb + KT_BYTES, r, h);
.Lnw_nomask:
	v_max3_f32 v192, v130, v131, v132
	v_max3_f32 v193, v133, v134, v135
	v_max3_f32 v175, v136, v137, v138
	v_max3_f32 v210, v139, v140, v141
	v_max3_f32 v192, v192, v142, v143
	v_max3_f32 v193, v193, v144, v145
	v_max3_f32 v175, v175, v114, v115
	v_max3_f32 v210, v210, v116, v117
	v_max3_f32 v192, v192, v118, v119
	v_max3_f32 v193, v193, v120, v121
	v_max3_f32 v175, v175, v122, v123
	v_max3_f32 v210, v210, v124, v125
	v_max3_f32 v192, v192, v126, v127
	v_max3_f32 v193, v193, v128, v129
	v_max3_f32 v192, v192, v193, v175
	v_max_f32_e32 v192, v192, v210
	v_mul_f32_e32 v192, s70, v192
	v_mov_b32_e32 v193, v192
	s_nop 1
	v_permlane32_swap_b32_e32 v192, v193
	v_max_f32_e32 v192, v192, v193
	v_sub_f32_e32 v193, v192, v211
	v_cmp_ge_f32_e32 vcc, s78, v193
	s_cmp_eq_u64 vcc, exec
	s_cbranch_scc1 .Lnw_nr
	v_max_f32_e32 v193, v211, v192
	v_sub_f32_e32 v192, v211, v193
	v_exp_f32_e32 v192, v192
	v_mov_b32_e32 v211, v193
	s_nop 0
	v_pk_mul_f32 v[112:113], v[112:113], v[192:193] op_sel_hi:[1,0]
	v_pk_mul_f32 v[110:111], v[110:111], v[192:193] op_sel_hi:[1,0]
	v_pk_mul_f32 v[108:109], v[108:109], v[192:193] op_sel_hi:[1,0]
	v_pk_mul_f32 v[106:107], v[106:107], v[192:193] op_sel_hi:[1,0]
	v_pk_mul_f32 v[104:105], v[104:105], v[192:193] op_sel_hi:[1,0]
	v_pk_mul_f32 v[102:103], v[102:103], v[192:193] op_sel_hi:[1,0]
	v_pk_mul_f32 v[100:101], v[100:101], v[192:193] op_sel_hi:[1,0]
	v_pk_mul_f32 v[98:99], v[98:99], v[192:193] op_sel_hi:[1,0]
	v_pk_mul_f32 v[96:97], v[96:97], v[192:193] op_sel_hi:[1,0]
	v_pk_mul_f32 v[94:95], v[94:95], v[192:193] op_sel_hi:[1,0]
	v_pk_mul_f32 v[92:93], v[92:93], v[192:193] op_sel_hi:[1,0]
	v_pk_mul_f32 v[90:91], v[90:91], v[192:193] op_sel_hi:[1,0]
	v_pk_mul_f32 v[88:89], v[88:89], v[192:193] op_sel_hi:[1,0]
	v_pk_mul_f32 v[86:87], v[86:87], v[192:193] op_sel_hi:[1,0]
	v_pk_mul_f32 v[84:85], v[84:85], v[192:193] op_sel_hi:[1,0]
	v_pk_mul_f32 v[82:83], v[82:83], v[192:193] op_sel_hi:[1,0]
	v_pk_mul_f32 v[80:81], v[80:81], v[192:193] op_sel_hi:[1,0]
	v_pk_mul_f32 v[78:79], v[78:79], v[192:193] op_sel_hi:[1,0]
	v_pk_mul_f32 v[76:77], v[76:77], v[192:193] op_sel_hi:[1,0]
	v_pk_mul_f32 v[74:75], v[74:75], v[192:193] op_sel_hi:[1,0]
	v_pk_mul_f32 v[72:73], v[72:73], v[192:193] op_sel_hi:[1,0]
	v_pk_mul_f32 v[70:71], v[70:71], v[192:193] op_sel_hi:[1,0]
	v_pk_mul_f32 v[68:69], v[68:69], v[192:193] op_sel_hi:[1,0]
	v_pk_mul_f32 v[66:67], v[66:67], v[192:193] op_sel_hi:[1,0]
.Lnw_nr:
	v_fma_f32 v130, v130, s70, -v211
	v_fma_f32 v131, v131, s70, -v211
	v_fma_f32 v132, v132, s70, -v211
	v_fma_f32 v133, v133, s70, -v211
	v_fma_f32 v134, v134, s70, -v211
	v_fma_f32 v135, v135, s70, -v211
	v_fma_f32 v136, v136, s70, -v211
	v_fma_f32 v137, v137, s70, -v211
	v_exp_f32_e32 v130, v130
	v_exp_f32_e32 v131, v131
	v_exp_f32_e32 v132, v132
	v_exp_f32_e32 v133, v133
	v_exp_f32_e32 v134, v134
	v_exp_f32_e32 v135, v135
	v_exp_f32_e32 v136, v136
	v_exp_f32_e32 v137, v137
	v_fma_f32 v138, v138, s70, -v211
	v_fma_f32 v139, v139, s70, -v211
	v_fma_f32 v140, v140, s70, -v211
	v_fma_f32 v141, v141, s70, -v211
	v_fma_f32 v142, v142, s70, -v211
	v_fma_f32 v143, v143, s70, -v211
	v_fma_f32 v144, v144, s70, -v211
	v_fma_f32 v145, v145, s70, -v211
	v_exp_f32_e32 v138, v138
	v_exp_f32_e32 v139, v139
	v_exp_f32_e32 v140, v140
	v_exp_f32_e32 v141, v141
	v_exp_f32_e32 v142, v142
	v_exp_f32_e32 v143, v143
	v_exp_f32_e32 v144, v144
	v_exp_f32_e32 v145, v145
	v_fma_f32 v114, v114, s70, -v211
	v_fma_f32 v115, v115, s70, -v211
	v_fma_f32 v116, v116, s70, -v211
	v_fma_f32 v117, v117, s70, -v211
	v_fma_f32 v118, v118, s70, -v211
	v_fma_f32 v119, v119, s70, -v211
	v_fma_f32 v120, v120, s70, -v211
	v_fma_f32 v121, v121, s70, -v211
	v_exp_f32_e32 v114, v114
	v_exp_f32_e32 v115, v115
	v_exp_f32_e32 v116, v116
	v_exp_f32_e32 v117, v117
	v_exp_f32_e32 v118, v118
	v_exp_f32_e32 v119, v119
	v_exp_f32_e32 v120, v120
	v_exp_f32_e32 v121, v121
	v_fma_f32 v122, v122, s70, -v211
	v_fma_f32 v123, v123, s70, -v211
	v_fma_f32 v124, v124, s70, -v211
	v_fma_f32 v125, v125, s70, -v211
	v_fma_f32 v126, v126, s70, -v211
	v_fma_f32 v127, v127, s70, -v211
	v_fma_f32 v128, v128, s70, -v211
	v_fma_f32 v129, v129, s70, -v211
	v_exp_f32_e32 v122, v122
	v_exp_f32_e32 v123, v123
	v_exp_f32_e32 v124, v124
	v_exp_f32_e32 v125, v125
	v_exp_f32_e32 v126, v126
	v_exp_f32_e32 v127, v127
	v_exp_f32_e32 v128, v128
	v_exp_f32_e32 v129, v129
	v_cvt_pk_bf16_f32 v212, v130, v131
	v_cvt_pk_bf16_f32 v213, v132, v133
	v_cvt_pk_bf16_f32 v214, v134, v135
	v_cvt_pk_bf16_f32 v215, v136, v137
	v_cvt_pk_bf16_f32 v216, v138, v139
	v_cvt_pk_bf16_f32 v217, v140, v141
	v_cvt_pk_bf16_f32 v218, v142, v143
	v_cvt_pk_bf16_f32 v219, v144, v145
	v_cvt_pk_bf16_f32 v220, v114, v115
	v_cvt_pk_bf16_f32 v221, v116, v117
	v_cvt_pk_bf16_f32 v222, v118, v119
	v_cvt_pk_bf16_f32 v223, v120, v121
	v_cvt_pk_bf16_f32 v224, v122, v123
	v_cvt_pk_bf16_f32 v225, v124, v125
	v_cvt_pk_bf16_f32 v226, v126, v127
	v_cvt_pk_bf16_f32 v227, v128, v129
	v_add_f32_e32 v130, v130, v114
	v_add_f32_e32 v131, v131, v115
	v_add_f32_e32 v98, v98, v130
	v_add_f32_e32 v132, v132, v116
	v_add_f32_e32 v99, v99, v131
	v_add_f32_e32 v133, v133, v117
	v_add_f32_e32 v100, v100, v132
	v_add_f32_e32 v134, v134, v118
	v_add_f32_e32 v101, v101, v133
	v_add_f32_e32 v135, v135, v119
	v_add_f32_e32 v102, v102, v134
	v_add_f32_e32 v136, v136, v120
	v_add_f32_e32 v103, v103, v135
	v_add_f32_e32 v137, v137, v121
	v_add_f32_e32 v104, v104, v136
	v_add_f32_e32 v138, v138, v122
	v_add_f32_e32 v105, v105, v137
	v_add_f32_e32 v139, v139, v123
	v_add_f32_e32 v106, v106, v138
	v_add_f32_e32 v140, v140, v124
	v_add_f32_e32 v107, v107, v139
	v_add_f32_e32 v141, v141, v125
	v_add_f32_e32 v108, v108, v140
	v_add_f32_e32 v142, v142, v126
	v_add_f32_e32 v109, v109, v141
	v_add_f32_e32 v143, v143, v127
	v_add_f32_e32 v110, v110, v142
	v_add_f32_e32 v144, v144, v128
	v_add_f32_e32 v111, v111, v143
	v_add_f32_e32 v145, v145, v129
	v_add_f32_e32 v112, v112, v144
	v_add_f32_e32 v113, v113, v145
.Lnw_xdone:
	s_waitcnt lgkmcnt(0)
	s_barrier
	s_add_i32 s26, s13, 1
	s_mov_b32 s17, 0
	s_cmp_ge_u32 s26, s12
	s_cbranch_scc1 .Lnw_y1
	s_add_i32 s15, s14, 1

;     ...
;             const int k0 = j * 64;
;             if (k0 > qb + 31 || k0 + 63 <= qb - 512) return;
	s_lshl_b32 s6, s15, 6
	s_add_i32 s7, s21, 31
	s_cmp_le_i32 s6, s7
	s_cselect_b32 s17, 1, 0
	s_add_i32 s6, s6, 63
	s_add_i32 s7, s21, 0xfffffe00
	s_cmp_gt_i32 s6, s7
	s_cselect_b32 s7, 1, 0
	s_and_b32 s17, s17, s7

;     ...
;     for (int i = 0; i < nt; ++i) {
;         const int j = jn;
;         const bool more = (i + 1 < nt);
;         if (more) { jn = next(j); if (probe != 1) kv_gload<DV, HAS_V>(st, Kb, VTb, ldv, jn * 64); }
;         if (probe != 2) body(j, (const unsigned char*)(lds + (i & 1) * SB));
.Lnw_y1:
	v_add3_u32 v237, s18, v204, v180
	v_add3_u32 v236, s19, v204, v180
	s_cmp_eq_u32 s16, 0
	s_cbranch_scc1 .Lnw_noa
	s_cmp_eq_u32 s17, 0
	s_cbranch_scc1 .Lnw_pvonly

; #define MFMA(a, b, c) __builtin_amdgcn_mfma_f32_32x32x16_bf16((a), (b), (c), 0, 0, 0)
; DI void attn_scores(const unsigned char* kb, const bf16x8 (&qf)[4], int r, int h, f32x16& s0, f32x16& s1) {
; #pragma unroll
;     for (int i = 0; i < 16; ++i) { s0[i] = 0.f; s1[i] = 0.f; }
; #pragma unroll
;     for (int s = 0; s < 4; ++s) {
;         const bf16x8 k0 = *(const bf16x8*)(kb + r * KP + s * 32 + h * 16);
;         const bf16x8 k1 = *(const bf16x8*)(kb + (32 + r) * KP + s * 32 + h * 16);
;         s0 = MFMA(k0, qf[s], s0); s1 = MFMA(k1, qf[s], s1);
;     }
; }
; template <int DV>
; DI void attn_pv(const unsigned char* vb, const bf16x8 (&pf)[2][2], int r, int h, f32x16 (&o)[DV / 32]) {
; #pragma unroll
;     for (int dt = 0; dt < DV / 32; ++dt)
; #pragma unroll
;         for (int mt = 0; mt < 2; ++mt)
; #pragma unroll
;             for (int sp = 0; sp < 2; ++sp) {
;                 const bf16x8 vf = *(const bf16x8*)(vb + (dt * 32 + r) * VP + (2 * mt + sp) * 32 + h * 16);
;                 o[dt] = MFMA(vf, pf[mt][sp], o[dt]);
;             }
; }
	ds_read_b128 v[228:231], v237 offset:9216
	ds_read_b128 v[232:235], v237 offset:9248
	ds_read_b128 v[206:209], v237 offset:9280
	s_waitcnt lgkmcnt(2)
	v_mfma_f32_32x32x16_bf16 v[82:97], v[228:231], v[212:215], v[82:97]
	ds_read_b128 v[228:231], v237 offset:9312
	s_waitcnt lgkmcnt(2)
	v_mfma_f32_32x32x16_bf16 v[82:97], v[232:235], v[216:219], v[82:97]
	ds_read_b128 v[232:235], v237 offset:13824
	s_waitcnt lgkmcnt(2)
	v_mfma_f32_32x32x16_bf16 v[82:97], v[206:209], v[220:223], v[82:97]
	ds_read_b128 v[206:209], v237 offset:13856
	s_waitcnt lgkmcnt(2)
	v_mfma_f32_32x32x16_bf16 v[82:97], v[228:231], v[224:227], v[82:97]
	ds_read_b128 v[228:231], v237 offset:13888
	s_waitcnt lgkmcnt(2)
	v_mfma_f32_32x32x16_bf16 v[66:81], v[232:235], v[212:215], v[66:81]
	ds_read_b128 v[232:235], v237 offset:13920
	s_waitcnt lgkmcnt(2)
	v_mfma_f32_32x32x16_bf16 v[66:81], v[206:209], v[216:219], v[66:81]
	ds_read_b128 v[206:209], v236 offset:0
	s_waitcnt lgkmcnt(2)
	v_mfma_f32_32x32x16_bf16 v[66:81], v[228:231], v[220:223], v[66:81]
	ds_read_b128 v[228:231], v236 offset:4608
	s_waitcnt lgkmcnt(2)
	v_mfma_f32_32x32x16_bf16 v[66:81], v[232:235], v[224:227], v[66:81]
	ds_read_b128 v[232:235], v236 offset:32
	s_waitcnt lgkmcnt(2)
	v_mfma_f32_32x32x16_bf16 v[130:145], v[206:209], v[146:149], 0
	ds_read_b128 v[206:209], v236 offset:4640
	s_waitcnt lgkmcnt(2)
	v_mfma_f32_32x32x16_bf16 v[114:129], v[228:231], v[146:149], 0
	ds_read_b128 v[228:231], v236 offset:64
	s_waitcnt lgkmcnt(2)
	v_mfma_f32_32x32x16_bf16 v[130:145], v[232:235], v[150:153], v[130:145]
	ds_read_b128 v[232:235], v236 offset:4672
	s_waitcnt lgkmcnt(2)
	v_mfma_f32_32x32x16_bf16 v[114:129], v[206:209], v[150:153], v[114:129]
	ds_read_b128 v[206:209], v236 offset:96
	s_waitcnt lgkmcnt(2)
	v_mfma_f32_32x32x16_bf16 v[130:145], v[228:231], v[154:157], v[130:145]
	ds_read_b128 v[228:231], v236 offset:4704
	s_waitcnt lgkmcnt(2)
	v_mfma_f32_32x32x16_bf16 v[114:129], v[232:235], v[154:157], v[114:129]
	s_waitcnt lgkmcnt(1)
	v_mfma_f32_32x32x16_bf16 v[130:145], v[206:209], v[158:161], v[130:145]
	s_waitcnt lgkmcnt(0)
	v_mfma_f32_32x32x16_bf16 v[114:129], v[228:231], v[158:161], v[114:129]
	s_branch .Lnw_stage
.Lnw_pvonly:
	ds_read_b128 v[228:231], v237 offset:9216
	ds_read_b128 v[232:235], v237 offset:9248
	ds_read_b128 v[206:209], v237 offset:9280
	s_waitcnt lgkmcnt(2)
	v_mfma_f32_32x32x16_bf16 v[82:97], v[228:231], v[212:215], v[82:97]
	ds_read_b128 v[228:231], v237 offset:9312
	s_waitcnt lgkmcnt(2)
	v_mfma_f32_32x32x16_bf16 v[82:97], v[232:235], v[216:219], v[82:97]
	ds_read_b128 v[232:235], v237 offset:13824
	s_waitcnt lgkmcnt(2)
	v_mfma_f32_32x32x16_bf16 v[82:97], v[206:209], v[220:223], v[82:97]
	ds_read_b128 v[206:209], v237 offset:13856
	s_waitcnt lgkmcnt(2)
	v_mfma_f32_32x32x16_bf16 v[82:97], v[228:231], v[224:227], v[82:97]
	ds_read_b128 v[228:231], v237 offset:13888
	s_waitcnt lgkmcnt(2)
	v_mfma_f32_32x32x16_bf16 v[66:81], v[232:235], v[212:215], v[66:81]
	ds_read_b128 v[232:235], v237 offset:13920
	s_waitcnt lgkmcnt(2)
	v_mfma_f32_32x32x16_bf16 v[66:81], v[206:209], v[216:219], v[66:81]
	s_waitcnt lgkmcnt(1)
	v_mfma_f32_32x32x16_bf16 v[66:81], v[228:231], v[220:223], v[66:81]
	s_waitcnt lgkmcnt(0)
	v_mfma_f32_32x32x16_bf16 v[66:81], v[232:235], v[224:227], v[66:81]
	s_branch .Lnw_stage
.Lnw_noa:
	s_cmp_eq_u32 s17, 0
	s_cbranch_scc1 .Lnw_stage
	ds_read_b128 v[228:231], v236 offset:0
	ds_read_b128 v[232:235], v236 offset:4608
	ds_read_b128 v[206:209], v236 offset:32
	s_waitcnt lgkmcnt(2)
	v_mfma_f32_32x32x16_bf16 v[130:145], v[228:231], v[146:149], 0
	ds_read_b128 v[228:231], v236 offset:4640
	s_waitcnt lgkmcnt(2)
	v_mfma_f32_32x32x16_bf16 v[114:129], v[232:235], v[146:149], 0
	ds_read_b128 v[232:235], v236 offset:64
	s_waitcnt lgkmcnt(2)
	v_mfma_f32_32x32x16_bf16 v[130:145], v[206:209], v[150:153], v[130:145]
	ds_read_b128 v[206:209], v236 offset:4672
	s_waitcnt lgkmcnt(2)
	v_mfma_f32_32x32x16_bf16 v[114:129], v[228:231], v[150:153], v[114:129]
	ds_read_b128 v[228:231], v236 offset:96
	s_waitcnt lgkmcnt(2)
	v_mfma_f32_32x32x16_bf16 v[130:145], v[232:235], v[154:157], v[130:145]
	ds_read_b128 v[232:235], v236 offset:4704
	s_waitcnt lgkmcnt(2)
	v_mfma_f32_32x32x16_bf16 v[114:129], v[206:209], v[154:157], v[114:129]
	s_waitcnt lgkmcnt(1)
	v_mfma_f32_32x32x16_bf16 v[130:145], v[228:231], v[158:161], v[130:145]
	s_waitcnt lgkmcnt(0)
	v_mfma_f32_32x32x16_bf16 v[114:129], v[232:235], v[158:161], v[114:129]
.Lnw_stage:
	s_add_i32 s26, s13, 2
	s_cmp_ge_u32 s26, s12
	s_cbranch_scc1 .Lnw_next
	s_waitcnt vmcnt(0)

; template <int DV, bool HAS_V>
; DI void kv_sstore(const KVStage<DV>& st, unsigned char* buf) {
;     const int tid = threadIdx.x;
;     *(u32x4*)(buf + (tid >> 3) * KP + (tid & 7) * 16) = st.k[0];
;     if (HAS_V) {
; #pragma unroll
;         for (int i = 0; i < DV / 64; ++i) {
;             const int c = tid + 512 * i, kc = c & 7; unsigned char* q = buf + KT_BYTES + (c >> 3) * VP + (kc >> 1) * 32 + (kc & 1) * 8;
;             u32x2 lo, hi; lo.x = st.v[i].x; lo.y = st.v[i].y; hi.x = st.v[i].z; hi.y = st.v[i].w;
;             *(u32x2*)q = lo; *(u32x2*)(q + 16) = hi;
;         }
;     }
; }
	v_add_u32_e32 v192, s20, v194
	v_add_u32_e32 v193, v192, v195
	v_add3_u32 v192, v192, v196, v197
	v_add_u32_e32 v192, 0x2000, v192
	ds_write_b128 v193, v[162:165]
	ds_write2_b64 v192, v[166:167], v[168:169] offset0:128 offset1:130

;     ...
;     for (int i = 0; i < nt; ++i) {
;         const int j = jn;
;         const bool more = (i + 1 < nt);
;         if (more) { jn = next(j); if (probe != 1) kv_gload<DV, HAS_V>(st, Kb, VTb, ldv, jn * 64); }
	s_add_i32 s26, s13, 3
	s_cmp_ge_u32 s26, s12
	s_cbranch_scc1 .Lnw_next
	s_add_i32 s15, s14, 3

; template <int DV, bool HAS_V>
; DI void kv_gload(KVStage<DV>& st, const bf16_t* __restrict__ Kb, const bf16_t* __restrict__ VTb, int ldv, int key0) {
;     const int tid = threadIdx.x;
;     st.k[0] = *(const u32x4*)(Kb + (size_t)(key0 + (tid >> 3)) * 64 + (tid & 7) * 8);
;     if (HAS_V) {
; #pragma unroll
;         for (int i = 0; i < DV / 64; ++i) { const int c = tid + 512 * i; st.v[i] = *(const u32x4*)(VTb + (size_t)(key0 >> 6) * (DV * 64) + c * 8); }
;     }
; }
	s_lshl_b32 s4, s15, 6
	v_add_u32_e32 v228, s4, v187
	v_mov_b32_e32 v229, v173
	v_lshlrev_b64 v[228:229], 7, v[228:229]
	v_lshl_add_u64 v[228:229], v[188:189], 0, v[228:229]
	global_load_dwordx4 v[162:165], v[228:229], off
	s_lshl_b32 s4, s15, 13
	s_mov_b32 s5, 0
	v_lshl_add_u64 v[230:231], v[190:191], 0, s[4:5]
	global_load_dwordx4 v[166:169], v[230:231], off

;     ...
;     for (int i = 0; i < nt; ++i) {
;         const int j = jn;
;         const bool more = (i + 1 < nt);
;         if (more) { jn = next(j); if (probe != 1) kv_gload<DV, HAS_V>(st, Kb, VTb, ldv, jn * 64); }
;         if (probe != 2) body(j, (const unsigned char*)(lds + (i & 1) * SB));
;         if (more && probe != 1) kv_sstore<DV, HAS_V>(st, lds + ((i + 1) & 1) * SB);
;         __syncthreads();
;     }
; }
.Lnw_next:
	s_add_i32 s14, s14, 1
	s_mov_b32 s16, s17
	s_mov_b32 s26, s18
	s_mov_b32 s18, s19
	s_mov_b32 s19, s20
	s_mov_b32 s20, s26
	s_add_i32 s13, s13, 1
	s_waitcnt lgkmcnt(0)
	s_barrier
	s_cmp_lt_u32 s13, s12
	s_cbranch_scc1 .Lnw_loop
	s_cmp_lg_u32 s28, 0
	s_cbranch_scc1 .LBB0_575
	s_barrier

